# v58 + attention accumulator-init subtractions as VOP2 (row bias kept negated)
# speedup vs baseline: 1.0034x; 1.0034x over previous
.LBB0_562:
	v_max3_f32 v32, v0, v23, v30
	v_max3_f32 v34, v2, v3, v33
	s_and_b32 s0, s15, 0x3fffffc0
	v_max3_f32 v32, v32, v28, v31
	v_max3_f32 v34, v34, v6, v7
	s_lshl_b32 s0, s0, 2
	v_max3_f32 v32, v32, v4, v5
	v_max3_f32 v34, v34, v24, v27
	s_add_i32 s85, s0, 0
	v_max3_f32 v32, v32, v26, v29
	v_max3_f32 v34, v34, v10, v11
	s_add_i32 s0, 0, 0x14800
	v_max3_f32 v32, v32, v8, v9
	v_max3_f32 v34, v34, v20, v21
	s_cmp_lg_u32 0, -1
	v_max3_f32 v32, v32, v22, v25
	v_max3_f32 v34, v34, v14, v15
	s_mov_b32 s15, 1
	v_max3_f32 v32, v32, v12, v13
	v_max3_f32 v34, v34, v16, v17
	s_mov_b32 s20, 0
	v_max3_f32 v32, v32, v18, v19
	v_lshl_add_u32 v214, v207, 2, s85
	v_max_f32_e32 v32, v32, v34
	s_nop 0
	v_mov_b32_e32 v34, v32
	s_nop 1
	v_permlane32_swap_b32_e32 v32, v34
	v_max_f32_e32 v32, v32, v34
	v_lshlrev_b32_e32 v34, 1, v48
	v_sub_f32_e32 v0, v0, v32
	v_sub_f32_e32 v30, v30, v32
	v_sub_f32_e32 v23, v23, v32
	v_sub_f32_e32 v33, v33, v32
	v_sub_f32_e32 v2, v2, v32
	v_sub_f32_e32 v28, v28, v32
	v_sub_f32_e32 v3, v3, v32
	v_sub_f32_e32 v31, v31, v32
	v_sub_f32_e32 v4, v4, v32
	v_sub_f32_e32 v26, v26, v32
	v_sub_f32_e32 v5, v5, v32
	v_sub_f32_e32 v29, v29, v32
	v_sub_f32_e32 v6, v6, v32
	v_sub_f32_e32 v24, v24, v32
	v_sub_f32_e32 v7, v7, v32
	v_sub_f32_e32 v27, v27, v32
	v_sub_f32_e32 v8, v8, v32
	v_sub_f32_e32 v22, v22, v32
	v_sub_f32_e32 v9, v9, v32
	v_sub_f32_e32 v25, v25, v32
	v_sub_f32_e32 v10, v10, v32
	v_sub_f32_e32 v20, v20, v32
	v_sub_f32_e32 v11, v11, v32
	v_sub_f32_e32 v21, v21, v32
	v_sub_f32_e32 v12, v12, v32
	v_sub_f32_e32 v18, v18, v32
	v_sub_f32_e32 v13, v13, v32
	v_sub_f32_e32 v19, v19, v32
	v_sub_f32_e32 v14, v14, v32
	v_sub_f32_e32 v16, v16, v32
	v_sub_f32_e32 v15, v15, v32
	v_sub_f32_e32 v17, v17, v32
	s_nop 0
	v_exp_f32_e32 v96, v0
	v_add_u32_e32 v0, s0, v217
	v_sub_f32_e64 v219, -v1, v32
	v_exp_f32_e32 v97, v23
	v_exp_f32_e32 v98, v2
	v_exp_f32_e32 v99, v3
	v_exp_f32_e32 v100, v4
	v_exp_f32_e32 v101, v5
	v_exp_f32_e32 v102, v6
	v_exp_f32_e32 v103, v7
	v_exp_f32_e32 v104, v8
	v_exp_f32_e32 v105, v9
	v_exp_f32_e32 v106, v10
	v_exp_f32_e32 v107, v11
	v_exp_f32_e32 v108, v12
	v_exp_f32_e32 v109, v13
	v_exp_f32_e32 v110, v14
	v_exp_f32_e32 v111, v15
	v_exp_f32_e32 v80, v30
	v_exp_f32_e32 v81, v33
	v_exp_f32_e32 v82, v28
	v_exp_f32_e32 v83, v31
	v_exp_f32_e32 v84, v26
	v_exp_f32_e32 v85, v29
	v_exp_f32_e32 v86, v24
	v_exp_f32_e32 v87, v27
	v_exp_f32_e32 v88, v22
	v_exp_f32_e32 v89, v25
	v_exp_f32_e32 v90, v20
	v_exp_f32_e32 v91, v21
	v_exp_f32_e32 v92, v18
	v_exp_f32_e32 v93, v19
	v_exp_f32_e32 v94, v16
	v_exp_f32_e32 v95, v17
	ds_read_b128 v[2:5], v0 offset:256
	ds_read_b128 v[6:9], v0 offset:288
	ds_read_b128 v[10:13], v0 offset:320
	ds_read_b128 v[14:17], v0 offset:352
	ds_read_b128 v[18:21], v0 offset:384
	ds_read_b128 v[22:25], v0 offset:416
	ds_read_b128 v[26:29], v0 offset:448
	ds_read_b128 v[30:33], v0 offset:480
	s_waitcnt vmcnt(0) lgkmcnt(0)
	s_barrier
	s_waitcnt lgkmcnt(7)
	v_sub_f32_e32 v65, v219, v3
	v_sub_f32_e32 v64, v219, v2
	v_lshl_add_u64 v[2:3], v[198:199], 0, s[40:41]
	s_mov_b32 s0, m0
	s_mov_b32 m0, s83
	s_nop 0
	global_load_lds_dwordx4 v[2:3], off
	s_mov_b32 m0, s0
	s_cselect_b32 s0, 0, 0
	s_add_i32 s0, s0, s14
	v_lshl_add_u64 v[2:3], v[200:201], 0, s[22:23]
	s_add_i32 s0, s0, 0x8000
	s_mov_b32 s1, m0
	s_mov_b32 m0, s0
	s_nop 0
	global_load_lds_dwordx4 v[2:3], off
	s_mov_b32 m0, s1
	ds_read_b128 v[172:175], v216 offset:8192
	ds_read_b128 v[168:171], v216 offset:8704
	ds_read_b128 v[164:167], v216 offset:10240
	ds_read_b128 v[160:163], v216 offset:10752
	ds_read_b128 v[156:159], v216 offset:12288
	ds_read_b128 v[152:155], v216 offset:12800
	ds_read_b128 v[148:151], v216 offset:14336
	ds_read_b128 v[144:147], v216 offset:14848
	v_and_b32_e32 v213, 32, v34
	v_lshlrev_b32_e32 v34, 4, v48
	v_and_b32_e32 v34, 0xc0, v34
	s_waitcnt vmcnt(2) lgkmcnt(0)
	s_barrier
	v_lshl_or_b32 v212, v208, 8, v34
	v_add_u32_e32 v34, 0, v213
	v_add3_u32 v218, v34, v209, v212
	s_waitcnt lgkmcnt(12)
	v_sub_f32_e32 v79, v219, v17
	v_sub_f32_e32 v78, v219, v16
	v_sub_f32_e32 v77, v219, v15
	v_sub_f32_e32 v76, v219, v14
	v_sub_f32_e32 v75, v219, v13
	v_sub_f32_e32 v74, v219, v12
	v_sub_f32_e32 v73, v219, v11
	v_sub_f32_e32 v72, v219, v10
	v_sub_f32_e32 v71, v219, v9
	v_sub_f32_e32 v70, v219, v8
	v_sub_f32_e32 v69, v219, v7
	v_sub_f32_e32 v68, v219, v6
	v_sub_f32_e32 v67, v219, v5
	v_sub_f32_e32 v66, v219, v4
	s_waitcnt lgkmcnt(8)
	v_sub_f32_e32 v63, v219, v33
	v_sub_f32_e32 v62, v219, v32
	v_sub_f32_e32 v61, v219, v31
	v_sub_f32_e32 v60, v219, v30
	v_sub_f32_e32 v59, v219, v29
	v_sub_f32_e32 v58, v219, v28
	v_sub_f32_e32 v57, v219, v27
	v_sub_f32_e32 v56, v219, v26
	v_sub_f32_e32 v55, v219, v25
	v_sub_f32_e32 v54, v219, v24
	v_sub_f32_e32 v53, v219, v23
	v_sub_f32_e32 v52, v219, v22
	v_sub_f32_e32 v51, v219, v21
	v_sub_f32_e32 v50, v219, v20
	v_sub_f32_e32 v49, v219, v19
	v_sub_f32_e32 v48, v219, v18
	s_cmp_lt_i32 s86, 7
	v_cmp_gt_u32_e64 s[0:1], 32, v206
	s_cbranch_scc1 .LBB0_578
	v_mov_b32_e32 v14, v1
	v_mov_b32_e32 v15, v1
	v_mov_b32_e32 v0, v1
	v_mov_b32_e32 v2, v1
	v_mov_b32_e32 v3, v1
	v_mov_b32_e32 v4, v1
	v_mov_b32_e32 v5, v1
	v_mov_b32_e32 v6, v1
	v_mov_b32_e32 v7, v1
	v_mov_b32_e32 v8, v1
	v_mov_b32_e32 v9, v1
	v_mov_b32_e32 v10, v1
	v_mov_b32_e32 v11, v1
	v_mov_b32_e32 v12, v1
	v_mov_b32_e32 v13, v1
	v_mov_b64_e32 v[46:47], v[14:15]
	v_mov_b64_e32 v[30:31], v[14:15]
	v_add_u32_e32 v188, s71, v217
	v_lshl_add_u64 v[184:185], v[200:201], 0, s[40:41]
	v_lshl_add_u64 v[186:187], v[198:199], 0, s[50:51]
	s_mov_b32 s15, 0
	s_movk_i32 s20, 0x4000
	s_movk_i32 s14, 0x2000
	v_mov_b32_e32 v220, 0
	s_mov_b32 s57, 6
	v_mov_b64_e32 v[44:45], v[12:13]
	v_mov_b64_e32 v[42:43], v[10:11]
	v_mov_b64_e32 v[40:41], v[8:9]
	v_mov_b64_e32 v[38:39], v[6:7]
	v_mov_b64_e32 v[36:37], v[4:5]
	v_mov_b64_e32 v[34:35], v[2:3]
	v_mov_b64_e32 v[32:33], v[0:1]
	v_mov_b64_e32 v[28:29], v[12:13]
	v_mov_b64_e32 v[26:27], v[10:11]
	v_mov_b64_e32 v[24:25], v[8:9]
	v_mov_b64_e32 v[22:23], v[6:7]
	v_mov_b64_e32 v[20:21], v[4:5]
	v_mov_b64_e32 v[18:19], v[2:3]
	v_mov_b64_e32 v[16:17], v[0:1]

.LBB0_567:
	s_add_i32 s15, s20, 0x2000
	s_cmpk_lg_i32 s20, 0x4000
	s_waitcnt lgkmcnt(10)
	v_sub_f32_e32 v111, v219, v111
	v_sub_f32_e32 v110, v219, v110
	v_sub_f32_e32 v109, v219, v109
	v_sub_f32_e32 v108, v219, v108
	v_sub_f32_e32 v107, v219, v107
	v_sub_f32_e32 v106, v219, v106
	v_sub_f32_e32 v105, v219, v105
	v_sub_f32_e32 v104, v219, v104
	v_sub_f32_e32 v103, v219, v183
	v_sub_f32_e32 v102, v219, v182
	v_sub_f32_e32 v101, v219, v181
	v_sub_f32_e32 v100, v219, v180
	v_sub_f32_e32 v99, v219, v171
	v_sub_f32_e32 v98, v219, v170
	v_sub_f32_e32 v97, v219, v169
	v_sub_f32_e32 v96, v219, v168
	s_waitcnt lgkmcnt(8)
	v_sub_f32_e32 v95, v219, v95
	v_sub_f32_e32 v94, v219, v94
	v_sub_f32_e32 v93, v219, v93
	v_sub_f32_e32 v92, v219, v92
	v_sub_f32_e32 v91, v219, v91
	v_sub_f32_e32 v90, v219, v90
	v_sub_f32_e32 v89, v219, v89
	v_sub_f32_e32 v88, v219, v88
	v_sub_f32_e32 v87, v219, v163
	v_sub_f32_e32 v86, v219, v162
	v_sub_f32_e32 v85, v219, v161
	v_sub_f32_e32 v84, v219, v160
	v_sub_f32_e32 v83, v219, v83
	v_sub_f32_e32 v82, v219, v82
	v_sub_f32_e32 v81, v219, v81
	v_sub_f32_e32 v80, v219, v80
	s_cselect_b32 s87, s15, 0
	v_add_u32_e32 v14, s14, v218
	ds_read_b64_tr_b16 v[168:169], v14 offset:24576
	ds_read_b64_tr_b16 v[170:171], v14 offset:25088
	s_waitcnt lgkmcnt(9)
	v_mfma_f32_32x32x16_bf16 v[96:111], v[164:167], v[124:127], v[96:111]
	v_add_f32_e32 v15, v64, v65
	v_add_f32_e32 v15, v66, v15
	v_add_f32_e32 v15, v67, v15
	v_add_f32_e32 v15, v68, v15
	v_add_f32_e32 v15, v69, v15
	v_cvt_pk_bf16_f32 v140, v64, v65
	v_cvt_pk_bf16_f32 v141, v66, v67
	ds_read_b64_tr_b16 v[160:161], v14 offset:28672
	ds_read_b64_tr_b16 v[162:163], v14 offset:29184
	s_waitcnt lgkmcnt(10)
	v_mfma_f32_32x32x16_bf16 v[80:95], v[152:155], v[124:127], v[80:95]
	v_add_f32_e32 v15, v70, v15
	v_add_f32_e32 v15, v71, v15
	v_add_f32_e32 v15, v72, v15
	v_add_f32_e32 v15, v73, v15
	v_cvt_pk_bf16_f32 v142, v68, v69
	v_cvt_pk_bf16_f32 v143, v70, v71
	ds_read_b64_tr_b16 v[152:153], v14 offset:25600
	ds_read_b64_tr_b16 v[154:155], v14 offset:26112
	s_waitcnt lgkmcnt(11)
	v_mfma_f32_32x32x16_bf16 v[96:111], v[156:159], v[120:123], v[96:111]
	v_add_f32_e32 v15, v74, v15
	v_add_f32_e32 v15, v75, v15
	v_add_f32_e32 v15, v76, v15
	v_add_f32_e32 v15, v77, v15
	v_cvt_pk_bf16_f32 v136, v72, v73
	v_cvt_pk_bf16_f32 v137, v74, v75
	ds_read_b64_tr_b16 v[72:73], v14 offset:29696
	ds_read_b64_tr_b16 v[74:75], v14 offset:30208
	s_waitcnt lgkmcnt(12)
	v_mfma_f32_32x32x16_bf16 v[80:95], v[144:147], v[120:123], v[80:95]
	v_add_f32_e32 v15, v78, v15
	v_add_f32_e32 v15, v79, v15
	v_add_f32_e32 v15, v48, v15
	v_add_f32_e32 v15, v49, v15
	v_cvt_pk_bf16_f32 v138, v76, v77
	v_cvt_pk_bf16_f32 v139, v78, v79
	ds_read_b64_tr_b16 v[68:69], v14 offset:26624
	ds_read_b64_tr_b16 v[70:71], v14 offset:27136
	s_waitcnt lgkmcnt(13)
	v_mfma_f32_32x32x16_bf16 v[96:111], v[148:151], v[116:119], v[96:111]
	v_add_f32_e32 v15, v50, v15
	v_add_f32_e32 v15, v51, v15
	v_add_f32_e32 v15, v52, v15
	v_add_f32_e32 v15, v53, v15
	v_cvt_pk_bf16_f32 v132, v48, v49
	v_cvt_pk_bf16_f32 v133, v50, v51
	ds_read_b64_tr_b16 v[64:65], v14 offset:30720
	ds_read_b64_tr_b16 v[66:67], v14 offset:31232
	s_waitcnt lgkmcnt(14)
	v_mfma_f32_32x32x16_bf16 v[80:95], v[6:9], v[116:119], v[80:95]
	v_add_f32_e32 v15, v54, v15
	v_add_f32_e32 v15, v55, v15
	v_add_f32_e32 v15, v56, v15
	v_add_f32_e32 v15, v57, v15
	v_cvt_pk_bf16_f32 v134, v52, v53
	v_cvt_pk_bf16_f32 v135, v54, v55
	ds_read_b64_tr_b16 v[48:49], v14 offset:27648
	ds_read_b64_tr_b16 v[50:51], v14 offset:28160
	s_waitcnt lgkmcnt(14)
	v_mfma_f32_32x32x16_bf16 v[96:111], v[10:13], v[112:115], v[96:111]
	v_add_f32_e32 v6, v58, v15
	v_add_f32_e32 v6, v59, v6
	v_add_f32_e32 v6, v60, v6
	v_add_f32_e32 v6, v61, v6
	v_cvt_pk_bf16_f32 v128, v56, v57
	v_cvt_pk_bf16_f32 v129, v58, v59
	ds_read_b64_tr_b16 v[10:11], v14 offset:31744
	ds_read_b64_tr_b16 v[12:13], v14 offset:32256
	v_mfma_f32_32x32x16_bf16 v[80:95], v[2:5], v[112:115], v[80:95]
	v_add_f32_e32 v6, v62, v6
	v_add_f32_e32 v6, v63, v6
	v_add_f32_e32 v6, 0, v6
	v_cvt_pk_bf16_f32 v130, v60, v61
	v_cvt_pk_bf16_f32 v131, v62, v63
	v_max_f32_e32 v2, v97, v97
	v_max_f32_e32 v3, v96, v96
	v_max_f32_e32 v2, v3, v2
	s_nop 3
	v_max3_f32 v3, v98, v99, v81
	v_max3_f32 v2, v2, v80, v82
	v_max3_f32 v2, v2, v83, v100
	v_max3_f32 v3, v3, v102, v103
	v_max3_f32 v2, v2, v101, v84
	v_max3_f32 v3, v3, v86, v87
	v_max3_f32 v2, v2, v85, v104
	v_max3_f32 v3, v3, v106, v107
	v_max3_f32 v2, v2, v105, v88
	v_max3_f32 v3, v3, v90, v91
	v_max3_f32 v2, v2, v89, v108
	v_max3_f32 v3, v3, v110, v111
	v_max3_f32 v2, v2, v109, v92
	v_max3_f32 v3, v3, v94, v95
	v_add_f32_e32 v220, v0, v6
	v_max3_f32 v0, v2, v93, v3
	v_mov_b32_e32 v2, v0
	s_nop 1
	v_permlane32_swap_b32_e32 v0, v2
	v_max_f32_e32 v2, v2, v2
	v_max_f32_e32 v0, v0, v0
	s_add_i32 s14, s20, s83
	s_mov_b32 s15, m0
	s_mov_b32 m0, s14
	s_nop 0
	global_load_lds_dwordx4 v[186:187], off
	s_mov_b32 m0, s15
	v_max_f32_e32 v0, v0, v2
	s_add_i32 s14, s87, s84
	s_mov_b32 s15, m0
	s_mov_b32 m0, s14
	s_nop 0
	global_load_lds_dwordx4 v[184:185], off
	s_mov_b32 m0, s15
	v_cmp_lt_f32_e32 vcc, s72, v0
	s_cmp_lg_u64 vcc, 0
	s_cselect_b64 s[60:61], -1, 0
	s_cbranch_vccnz .LBB0_575

.LBB0_570:
	s_add_i32 s14, s87, 0x2000
	s_cmpk_lg_i32 s87, 0x4000
	s_cselect_b32 s56, s14, 0
	s_add_i32 s14, s57, 2
	s_waitcnt lgkmcnt(10)
	v_sub_f32_e32 v79, v219, v79
	v_sub_f32_e32 v78, v219, v78
	v_sub_f32_e32 v77, v219, v77
	v_sub_f32_e32 v76, v219, v76
	v_sub_f32_e32 v75, v219, v183
	v_sub_f32_e32 v74, v219, v182
	v_sub_f32_e32 v73, v219, v181
	v_sub_f32_e32 v72, v219, v180
	v_sub_f32_e32 v71, v219, v179
	v_sub_f32_e32 v70, v219, v178
	v_sub_f32_e32 v69, v219, v177
	v_sub_f32_e32 v68, v219, v176
	v_sub_f32_e32 v67, v219, v63
	v_sub_f32_e32 v66, v219, v62
	v_sub_f32_e32 v65, v219, v61
	v_sub_f32_e32 v64, v219, v60
	s_waitcnt lgkmcnt(8)
	v_sub_f32_e32 v63, v219, v59
	v_sub_f32_e32 v62, v219, v58
	v_sub_f32_e32 v61, v219, v57
	v_sub_f32_e32 v60, v219, v56
	v_sub_f32_e32 v59, v219, v55
	v_sub_f32_e32 v58, v219, v54
	v_sub_f32_e32 v57, v219, v53
	v_sub_f32_e32 v56, v219, v52
	v_sub_f32_e32 v55, v219, v9
	v_sub_f32_e32 v54, v219, v8
	v_sub_f32_e32 v53, v219, v7
	v_sub_f32_e32 v52, v219, v6
	v_sub_f32_e32 v51, v219, v5
	v_sub_f32_e32 v50, v219, v4
	v_sub_f32_e32 v49, v219, v3
	v_sub_f32_e32 v48, v219, v2
	v_add_u32_e32 v188, 0x200, v188
	v_lshl_add_u64 v[184:185], v[184:185], 0, s[24:25]
	s_cmp_ge_i32 s14, s86
	v_lshl_add_u64 v[186:187], v[186:187], 0, s[24:25]
	s_cbranch_scc1 .LBB0_594
	s_mov_b32 s57, s14
	s_mov_b32 s15, s20
	s_mov_b32 s14, s87
	s_mov_b32 s20, s56
	s_branch .LBB0_564
.LBB0_572:
	v_max_f32_e32 v14, v14, v14
	v_max_f32_e32 v15, 0, v14
	v_exp_f32_e64 v14, -v15
	s_and_saveexec_b64 s[62:63], s[0:1]
	ds_write_b32 v214, v14 offset:49152
	s_or_b64 exec, exec, s[62:63]
	v_sub_f32_e32 v79, v79, v15
	v_sub_f32_e32 v78, v78, v15
	v_sub_f32_e32 v77, v77, v15
	v_sub_f32_e32 v76, v76, v15
	v_sub_f32_e32 v75, v75, v15
	v_sub_f32_e32 v74, v74, v15
	v_sub_f32_e32 v73, v73, v15
	v_sub_f32_e32 v72, v72, v15
	v_sub_f32_e32 v71, v71, v15
	v_sub_f32_e32 v70, v70, v15
	v_sub_f32_e32 v69, v69, v15
	v_sub_f32_e32 v68, v68, v15
	v_sub_f32_e32 v67, v67, v15
	v_sub_f32_e32 v66, v66, v15
	v_sub_f32_e32 v65, v65, v15
	v_sub_f32_e32 v64, v64, v15
	v_sub_f32_e32 v63, v63, v15
	v_sub_f32_e32 v62, v62, v15
	v_sub_f32_e32 v61, v61, v15
	v_sub_f32_e32 v60, v60, v15
	v_sub_f32_e32 v59, v59, v15
	v_sub_f32_e32 v58, v58, v15
	v_sub_f32_e32 v57, v57, v15
	v_sub_f32_e32 v56, v56, v15
	v_sub_f32_e32 v55, v55, v15
	v_sub_f32_e32 v54, v54, v15
	v_sub_f32_e32 v53, v53, v15
	v_sub_f32_e32 v52, v52, v15
	v_sub_f32_e32 v51, v51, v15
	v_sub_f32_e32 v50, v50, v15
	v_sub_f32_e32 v49, v49, v15
	v_sub_f32_e32 v48, v48, v15
	v_sub_f32_e32 v219, v219, v15
	v_mul_f32_e32 v0, v0, v14
	s_branch .LBB0_565
.LBB0_575:
	v_max_f32_e32 v0, v0, v0
	v_max_f32_e32 v2, 0, v0
	v_exp_f32_e64 v0, -v2
	s_and_saveexec_b64 s[62:63], s[0:1]
	ds_write_b32 v214, v0 offset:49152
	s_or_b64 exec, exec, s[62:63]
	v_sub_f32_e32 v111, v111, v2
	v_sub_f32_e32 v110, v110, v2
	v_sub_f32_e32 v109, v109, v2
	v_sub_f32_e32 v108, v108, v2
	v_sub_f32_e32 v107, v107, v2
	v_sub_f32_e32 v106, v106, v2
	v_sub_f32_e32 v105, v105, v2
	v_sub_f32_e32 v104, v104, v2
	v_sub_f32_e32 v103, v103, v2
	v_sub_f32_e32 v102, v102, v2
	v_sub_f32_e32 v101, v101, v2
	v_sub_f32_e32 v100, v100, v2
	v_sub_f32_e32 v99, v99, v2
	v_sub_f32_e32 v98, v98, v2
	v_sub_f32_e32 v97, v97, v2
	v_sub_f32_e32 v96, v96, v2
	v_sub_f32_e32 v95, v95, v2
	v_sub_f32_e32 v94, v94, v2
	v_sub_f32_e32 v93, v93, v2
	v_sub_f32_e32 v92, v92, v2
	v_sub_f32_e32 v91, v91, v2
	v_sub_f32_e32 v90, v90, v2
	v_sub_f32_e32 v89, v89, v2
	v_sub_f32_e32 v88, v88, v2
	v_sub_f32_e32 v87, v87, v2
	v_sub_f32_e32 v86, v86, v2
	v_sub_f32_e32 v85, v85, v2
	v_sub_f32_e32 v84, v84, v2
	v_sub_f32_e32 v83, v83, v2
	v_sub_f32_e32 v82, v82, v2
	v_sub_f32_e32 v81, v81, v2
	v_sub_f32_e32 v80, v80, v2
	v_sub_f32_e32 v219, v219, v2
	v_mul_f32_e32 v220, v220, v0
	s_branch .LBB0_568

.LBB0_605:
	s_waitcnt lgkmcnt(10)
	v_sub_f32_e32 v111, v219, v111
	v_sub_f32_e32 v110, v219, v110
	v_sub_f32_e32 v109, v219, v109
	v_sub_f32_e32 v108, v219, v108
	v_sub_f32_e32 v107, v219, v107
	v_sub_f32_e32 v106, v219, v106
	v_sub_f32_e32 v105, v219, v105
	v_sub_f32_e32 v104, v219, v104
	v_sub_f32_e32 v103, v219, v191
	v_sub_f32_e32 v102, v219, v190
	v_sub_f32_e32 v101, v219, v189
	v_sub_f32_e32 v100, v219, v188
	v_sub_f32_e32 v99, v219, v187
	v_sub_f32_e32 v98, v219, v186
	v_sub_f32_e32 v97, v219, v185
	v_sub_f32_e32 v96, v219, v184
	s_waitcnt lgkmcnt(8)
	v_sub_f32_e32 v95, v219, v95
	v_sub_f32_e32 v94, v219, v94
	v_sub_f32_e32 v93, v219, v93
	v_sub_f32_e32 v92, v219, v92
	v_sub_f32_e32 v91, v219, v91
	v_sub_f32_e32 v90, v219, v90
	v_sub_f32_e32 v89, v219, v89
	v_sub_f32_e32 v88, v219, v88
	v_sub_f32_e32 v87, v219, v87
	v_sub_f32_e32 v86, v219, v86
	v_sub_f32_e32 v85, v219, v85
	v_sub_f32_e32 v84, v219, v84
	v_sub_f32_e32 v83, v219, v83
	v_sub_f32_e32 v82, v219, v82
	v_sub_f32_e32 v81, v219, v81
	v_sub_f32_e32 v80, v219, v80
	v_add_u32_e32 v4, s87, v218
	ds_read_b64_tr_b16 v[192:193], v4 offset:24576
	ds_read_b64_tr_b16 v[194:195], v4 offset:25088
	s_waitcnt lgkmcnt(9)
	v_mfma_f32_32x32x16_bf16 v[96:111], v[172:175], v[124:127], v[96:111]
	v_add_f32_e32 v2, v64, v65
	v_add_f32_e32 v2, v66, v2
	v_add_f32_e32 v2, v67, v2
	v_add_f32_e32 v2, v68, v2
	v_add_f32_e32 v2, v69, v2
	v_cvt_pk_bf16_f32 v140, v64, v65
	v_cvt_pk_bf16_f32 v141, v66, v67
	ds_read_b64_tr_b16 v[188:189], v4 offset:28672
	ds_read_b64_tr_b16 v[190:191], v4 offset:29184
	s_waitcnt lgkmcnt(10)
	v_mfma_f32_32x32x16_bf16 v[80:95], v[168:171], v[124:127], v[80:95]
	v_add_f32_e32 v2, v70, v2
	v_add_f32_e32 v2, v71, v2
	v_add_f32_e32 v2, v72, v2
	v_add_f32_e32 v2, v73, v2
	v_cvt_pk_bf16_f32 v142, v68, v69
	v_cvt_pk_bf16_f32 v143, v70, v71
	ds_read_b64_tr_b16 v[184:185], v4 offset:25600
	ds_read_b64_tr_b16 v[186:187], v4 offset:26112
	s_waitcnt lgkmcnt(11)
	v_mfma_f32_32x32x16_bf16 v[96:111], v[164:167], v[120:123], v[96:111]
	v_add_f32_e32 v2, v74, v2
	v_add_f32_e32 v2, v75, v2
	v_add_f32_e32 v2, v76, v2
	v_add_f32_e32 v2, v77, v2
	v_cvt_pk_bf16_f32 v136, v72, v73
	v_cvt_pk_bf16_f32 v137, v74, v75
	ds_read_b64_tr_b16 v[180:181], v4 offset:29696
	ds_read_b64_tr_b16 v[182:183], v4 offset:30208
	s_waitcnt lgkmcnt(12)
	v_mfma_f32_32x32x16_bf16 v[80:95], v[160:163], v[120:123], v[80:95]
	v_add_f32_e32 v2, v78, v2
	v_add_f32_e32 v2, v79, v2
	v_add_f32_e32 v2, v48, v2
	v_add_f32_e32 v2, v49, v2
	v_cvt_pk_bf16_f32 v138, v76, v77
	v_cvt_pk_bf16_f32 v139, v78, v79
	ds_read_b64_tr_b16 v[176:177], v4 offset:26624
	ds_read_b64_tr_b16 v[178:179], v4 offset:27136
	s_waitcnt lgkmcnt(13)
	v_mfma_f32_32x32x16_bf16 v[96:111], v[156:159], v[116:119], v[96:111]
	v_add_f32_e32 v2, v50, v2
	v_add_f32_e32 v2, v51, v2
	v_add_f32_e32 v2, v52, v2
	v_add_f32_e32 v2, v53, v2
	v_cvt_pk_bf16_f32 v132, v48, v49
	v_cvt_pk_bf16_f32 v133, v50, v51
	ds_read_b64_tr_b16 v[10:11], v4 offset:30720
	ds_read_b64_tr_b16 v[12:13], v4 offset:31232
	s_waitcnt lgkmcnt(14)
	v_mfma_f32_32x32x16_bf16 v[80:95], v[152:155], v[116:119], v[80:95]
	v_add_f32_e32 v2, v54, v2
	v_add_f32_e32 v2, v55, v2
	v_add_f32_e32 v2, v56, v2
	v_add_f32_e32 v2, v57, v2
	v_cvt_pk_bf16_f32 v134, v52, v53
	v_cvt_pk_bf16_f32 v135, v54, v55
	ds_read_b64_tr_b16 v[6:7], v4 offset:27648
	ds_read_b64_tr_b16 v[8:9], v4 offset:28160
	s_waitcnt lgkmcnt(14)
	v_mfma_f32_32x32x16_bf16 v[96:111], v[148:151], v[112:115], v[96:111]
	v_add_f32_e32 v2, v58, v2
	v_add_f32_e32 v2, v59, v2
	v_add_f32_e32 v2, v60, v2
	v_add_f32_e32 v221, v61, v2
	v_cvt_pk_bf16_f32 v128, v56, v57
	v_cvt_pk_bf16_f32 v129, v58, v59
	ds_read_b64_tr_b16 v[2:3], v4 offset:31744
	ds_read_b64_tr_b16 v[4:5], v4 offset:32256
	v_mfma_f32_32x32x16_bf16 v[80:95], v[144:147], v[112:115], v[80:95]
	v_add_f32_e32 v130, v62, v221
	v_add_f32_e32 v130, v63, v130
	v_add_f32_e32 v221, 0, v130
	v_cvt_pk_bf16_f32 v130, v60, v61
	v_cvt_pk_bf16_f32 v131, v62, v63
	s_add_i32 s20, s10, 2
	s_cmp_ge_i32 s20, s86
	s_cselect_b64 s[62:63], -1, 0
	s_and_b64 vcc, exec, s[62:63]
	s_cbranch_vccnz .LBB0_607
	s_lshl_b64 s[64:65], s[20:21], 17
	v_lshl_add_u64 v[222:223], v[198:199], 0, s[64:65]
	s_add_i32 s11, s56, s83
	s_mov_b32 s15, m0
	s_mov_b32 m0, s11
	s_nop 0
	global_load_lds_dwordx4 v[222:223], off
	s_mov_b32 m0, s15

.LBB0_635:
	v_sub_f32_e32 v79, v219, v79
	v_sub_f32_e32 v78, v219, v78
	v_sub_f32_e32 v77, v219, v77
	v_sub_f32_e32 v76, v219, v76
	v_sub_f32_e32 v75, v219, v75
	v_sub_f32_e32 v74, v219, v74
	v_sub_f32_e32 v73, v219, v73
	v_sub_f32_e32 v72, v219, v72
	v_sub_f32_e32 v71, v219, v71
	v_sub_f32_e32 v70, v219, v70
	v_sub_f32_e32 v69, v219, v69
	v_sub_f32_e32 v68, v219, v68
	v_sub_f32_e32 v67, v219, v67
	v_sub_f32_e32 v66, v219, v66
	v_sub_f32_e32 v65, v219, v65
	v_sub_f32_e32 v64, v219, v64
	v_sub_f32_e32 v63, v219, v63
	v_sub_f32_e32 v62, v219, v62
	v_sub_f32_e32 v61, v219, v61
	v_sub_f32_e32 v60, v219, v60
	v_sub_f32_e32 v59, v219, v59
	v_sub_f32_e32 v58, v219, v58
	v_sub_f32_e32 v57, v219, v57
	v_sub_f32_e32 v56, v219, v56
	v_sub_f32_e32 v55, v219, v55
	v_sub_f32_e32 v54, v219, v54
	v_sub_f32_e32 v53, v219, v53
	v_sub_f32_e32 v52, v219, v52
	v_sub_f32_e32 v51, v219, v51
	v_sub_f32_e32 v50, v219, v50
	v_sub_f32_e32 v49, v219, v49
	v_sub_f32_e32 v48, v219, v48
	s_mov_b64 s[10:11], -1
	s_and_b64 vcc, exec, s[62:63]
	s_cbranch_vccz .LBB0_624

.LBB0_642:
	v_max_f32_e32 v15, v15, v15
	v_max_f32_e32 v80, 0, v15
	v_exp_f32_e64 v15, -v80
	s_and_saveexec_b64 s[64:65], s[0:1]
	ds_write_b32 v214, v15 offset:49152
	s_or_b64 exec, exec, s[64:65]
	v_sub_f32_e32 v79, v79, v80
	v_sub_f32_e32 v78, v78, v80
	v_sub_f32_e32 v77, v77, v80
	v_sub_f32_e32 v76, v76, v80
	v_sub_f32_e32 v75, v75, v80
	v_sub_f32_e32 v74, v74, v80
	v_sub_f32_e32 v73, v73, v80
	v_sub_f32_e32 v72, v72, v80
	v_sub_f32_e32 v71, v71, v80
	v_sub_f32_e32 v70, v70, v80
	v_sub_f32_e32 v69, v69, v80
	v_sub_f32_e32 v68, v68, v80
	v_sub_f32_e32 v67, v67, v80
	v_sub_f32_e32 v66, v66, v80
	v_sub_f32_e32 v65, v65, v80
	v_sub_f32_e32 v64, v64, v80
	v_sub_f32_e32 v63, v63, v80
	v_sub_f32_e32 v62, v62, v80
	v_sub_f32_e32 v61, v61, v80
	v_sub_f32_e32 v60, v60, v80
	v_sub_f32_e32 v59, v59, v80
	v_sub_f32_e32 v58, v58, v80
	v_sub_f32_e32 v57, v57, v80
	v_sub_f32_e32 v56, v56, v80
	v_sub_f32_e32 v55, v55, v80
	v_sub_f32_e32 v54, v54, v80
	v_sub_f32_e32 v53, v53, v80
	v_sub_f32_e32 v52, v52, v80
	v_sub_f32_e32 v51, v51, v80
	v_sub_f32_e32 v50, v50, v80
	v_sub_f32_e32 v49, v49, v80
	v_sub_f32_e32 v48, v48, v80
	v_sub_f32_e32 v219, v219, v80
	v_mul_f32_e32 v220, v220, v15
	s_branch .LBB0_601
.LBB0_645:
	v_max_f32_e32 v221, v221, v221
	v_max_f32_e32 v222, 0, v221
	v_exp_f32_e64 v221, -v222
	s_and_saveexec_b64 s[10:11], s[0:1]
	ds_write_b32 v214, v221 offset:49152
	s_or_b64 exec, exec, s[10:11]
	v_sub_f32_e32 v111, v111, v222
	v_sub_f32_e32 v110, v110, v222
	v_sub_f32_e32 v109, v109, v222
	v_sub_f32_e32 v108, v108, v222
	v_sub_f32_e32 v107, v107, v222
	v_sub_f32_e32 v106, v106, v222
	v_sub_f32_e32 v105, v105, v222
	v_sub_f32_e32 v104, v104, v222
	v_sub_f32_e32 v103, v103, v222
	v_sub_f32_e32 v102, v102, v222
	v_sub_f32_e32 v101, v101, v222
	v_sub_f32_e32 v100, v100, v222
	v_sub_f32_e32 v99, v99, v222
	v_sub_f32_e32 v98, v98, v222
	v_sub_f32_e32 v97, v97, v222
	v_sub_f32_e32 v96, v96, v222
	v_sub_f32_e32 v95, v95, v222
	v_sub_f32_e32 v94, v94, v222
	v_sub_f32_e32 v93, v93, v222
	v_sub_f32_e32 v92, v92, v222
	v_sub_f32_e32 v91, v91, v222
	v_sub_f32_e32 v90, v90, v222
	v_sub_f32_e32 v89, v89, v222
	v_sub_f32_e32 v88, v88, v222
	v_sub_f32_e32 v87, v87, v222
	v_sub_f32_e32 v86, v86, v222
	v_sub_f32_e32 v85, v85, v222
	v_sub_f32_e32 v84, v84, v222
	v_sub_f32_e32 v83, v83, v222
	v_sub_f32_e32 v82, v82, v222
	v_sub_f32_e32 v81, v81, v222
	v_sub_f32_e32 v80, v80, v222
	v_sub_f32_e32 v219, v219, v222
	v_mul_f32_e32 v220, v220, v221
	s_branch .LBB0_612
